# v76 + XCD-local barriers in all-to-all flag form (each workgroup stores its flag and polls the group's 32-word line; no atomics, no leader hop)
# speedup vs baseline: 1.0013x; 1.0013x over previous
.LBB0_233:
	s_mov_b64 s[6:7], s[0:1]
	s_getreg_b32 s8, hwreg(HW_REG_XCC_ID, 0, 4)
	s_waitcnt vmcnt(0)
	s_waitcnt vmcnt(0)
	v_add_u32_e32 v254, v254, v255
	v_cmp_ne_u32_e32 vcc, 17, v254
	s_nop 3
	s_cmp_eq_u64 vcc, 0
	s_cselect_b32 s99, 1, 0
	s_cmpk_lg_i32 s52, 0x100
	s_cselect_b32 s99, 0, s99
	s_barrier
	s_and_saveexec_b64 s[4:5], s[44:45]
	s_xor_b64 s[4:5], exec, s[4:5]
	s_cbranch_execz .LBB0_286
	s_cmp_eq_u32 s99, 0
	s_cbranch_scc1 .Lfb_skip_0
	s_load_dwordx2 s[8:9], s[0:1], 0x80
	s_and_b32 s10, s2, 7
	s_lshl_b32 s10, s10, 8
	s_add_i32 s10, s10, 0x1000
	s_lshr_b32 s11, s2, 3
	s_lshl_b32 s11, s11, 2
	v_mov_b32_e32 v1, s11
	v_mov_b32_e32 v0, 1
	s_mov_b32 s13, 0
	s_mov_b64 s[16:17], exec
	s_waitcnt lgkmcnt(0)
	s_add_u32 s8, s8, s10
	s_addc_u32 s9, s9, 0
	global_store_dword v1, v0, s[8:9]
	buffer_inv sc1
	s_mov_b64 exec, 0xffffffff
	v_mbcnt_lo_u32_b32 v4, -1, 0
	v_lshlrev_b32_e32 v4, 2, v4
	v_mov_b32_e32 v0, 1

.Lfb_done_0:
	s_mov_b64 exec, s[16:17]
	s_waitcnt vmcnt(0)
	s_branch .LBB0_286

.LBB0_518:
	s_mov_b64 s[6:7], s[0:1]
	s_getreg_b32 s8, hwreg(HW_REG_XCC_ID, 0, 4)
	s_waitcnt vmcnt(0)
	s_barrier
	s_and_saveexec_b64 s[4:5], s[44:45]
	s_cbranch_execz .LBB0_570
	s_cmp_eq_u32 s99, 0
	s_cbranch_scc1 .Lfb_skip_1
	s_load_dwordx2 s[8:9], s[0:1], 0x80
	s_and_b32 s10, s2, 7
	s_lshl_b32 s10, s10, 8
	s_add_i32 s10, s10, 0x1000
	s_lshr_b32 s11, s2, 3
	s_lshl_b32 s11, s11, 2
	v_mov_b32_e32 v1, s11
	v_mov_b32_e32 v0, 2
	s_mov_b32 s13, 0
	s_mov_b64 s[16:17], exec
	s_waitcnt lgkmcnt(0)
	s_add_u32 s8, s8, s10
	s_addc_u32 s9, s9, 0
	global_store_dword v1, v0, s[8:9]
	buffer_inv sc1
	s_mov_b64 exec, 0xffffffff
	v_mbcnt_lo_u32_b32 v4, -1, 0
	v_lshlrev_b32_e32 v4, 2, v4
	v_mov_b32_e32 v0, 2

.LBB0_612:
	s_mov_b64 s[8:9], s[0:1]
	s_waitcnt lgkmcnt(0)
	s_getreg_b32 s10, hwreg(HW_REG_XCC_ID, 0, 4)
	s_waitcnt vmcnt(0)
	s_barrier
	s_and_saveexec_b64 s[6:7], s[44:45]
	s_cbranch_execz .LBB0_664
	s_cmp_eq_u32 s99, 0
	s_cbranch_scc1 .Lfb_skip_2
	s_load_dwordx2 s[8:9], s[0:1], 0x80
	s_and_b32 s10, s2, 7
	s_lshl_b32 s10, s10, 8
	s_add_i32 s10, s10, 0x1000
	s_lshr_b32 s11, s2, 3
	s_lshl_b32 s11, s11, 2
	v_mov_b32_e32 v1, s11
	v_mov_b32_e32 v0, 3
	s_mov_b32 s13, 0
	s_mov_b64 s[16:17], exec
	s_waitcnt lgkmcnt(0)
	s_add_u32 s8, s8, s10
	s_addc_u32 s9, s9, 0
	global_store_dword v1, v0, s[8:9]
	buffer_inv sc1
	s_mov_b64 exec, 0xffffffff
	v_mbcnt_lo_u32_b32 v4, -1, 0
	v_lshlrev_b32_e32 v4, 2, v4
	v_mov_b32_e32 v0, 3

.LBB0_1112:
	s_mov_b64 s[8:9], s[0:1]
	s_getreg_b32 s10, hwreg(HW_REG_XCC_ID, 0, 4)
	s_waitcnt vmcnt(0)
	s_barrier
	s_and_saveexec_b64 s[6:7], s[44:45]
	s_cbranch_execz .LBB0_1164
	s_cmp_eq_u32 s99, 0
	s_cbranch_scc1 .Lfb_skip_3
	s_load_dwordx2 s[8:9], s[0:1], 0x80
	s_and_b32 s10, s2, 7
	s_lshl_b32 s10, s10, 8
	s_add_i32 s10, s10, 0x1000
	s_lshr_b32 s11, s2, 3
	s_lshl_b32 s11, s11, 2
	v_mov_b32_e32 v1, s11
	v_mov_b32_e32 v0, 4
	s_mov_b32 s13, 0
	s_mov_b64 s[16:17], exec
	s_waitcnt lgkmcnt(0)
	s_add_u32 s8, s8, s10
	s_addc_u32 s9, s9, 0
	global_store_dword v1, v0, s[8:9]
	buffer_inv sc1
	s_mov_b64 exec, 0xffffffff
	v_mbcnt_lo_u32_b32 v4, -1, 0
	v_lshlrev_b32_e32 v4, 2, v4
	v_mov_b32_e32 v0, 4

.LBB0_1210:
	s_mov_b64 s[8:9], s[0:1]
	s_getreg_b32 s10, hwreg(HW_REG_XCC_ID, 0, 4)
	s_waitcnt vmcnt(0)
	s_waitcnt lgkmcnt(0)
	s_barrier
	s_and_saveexec_b64 s[6:7], s[44:45]
	s_cbranch_execz .LBB0_1262
	s_cmp_eq_u32 s99, 0
	s_cbranch_scc1 .Lfb_skip_4
	s_load_dwordx2 s[8:9], s[0:1], 0x80
	s_and_b32 s10, s2, 7
	s_lshl_b32 s10, s10, 8
	s_add_i32 s10, s10, 0x1000
	s_lshr_b32 s11, s2, 3
	s_lshl_b32 s11, s11, 2
	v_mov_b32_e32 v1, s11
	v_mov_b32_e32 v0, 5
	s_mov_b32 s13, 0
	s_mov_b64 s[16:17], exec
	s_waitcnt lgkmcnt(0)
	s_add_u32 s8, s8, s10
	s_addc_u32 s9, s9, 0
	global_store_dword v1, v0, s[8:9]
	buffer_inv sc1
	s_mov_b64 exec, 0xffffffff
	v_mbcnt_lo_u32_b32 v4, -1, 0
	v_lshlrev_b32_e32 v4, 2, v4
	v_mov_b32_e32 v0, 5

.LBB0_1349:
	s_mov_b64 s[8:9], s[0:1]
	s_getreg_b32 s10, hwreg(HW_REG_XCC_ID, 0, 4)
	s_waitcnt vmcnt(0)
	s_barrier
	s_and_saveexec_b64 s[6:7], s[44:45]
	s_cbranch_execz .LBB0_1401
	s_cmp_eq_u32 s99, 0
	s_cbranch_scc1 .Lfb_skip_5
	s_load_dwordx2 s[8:9], s[0:1], 0x80
	s_and_b32 s10, s2, 7
	s_lshl_b32 s10, s10, 8
	s_add_i32 s10, s10, 0x1000
	s_lshr_b32 s11, s2, 3
	s_lshl_b32 s11, s11, 2
	v_mov_b32_e32 v1, s11
	v_mov_b32_e32 v0, 6
	s_mov_b32 s13, 0
	s_mov_b64 s[16:17], exec
	s_waitcnt lgkmcnt(0)
	s_add_u32 s8, s8, s10
	s_addc_u32 s9, s9, 0
	global_store_dword v1, v0, s[8:9]
	buffer_inv sc1
	s_mov_b64 exec, 0xffffffff
	v_mbcnt_lo_u32_b32 v4, -1, 0
	v_lshlrev_b32_e32 v4, 2, v4
	v_mov_b32_e32 v0, 6

.LBB0_1443:
	s_mov_b64 s[8:9], s[0:1]
	s_getreg_b32 s10, hwreg(HW_REG_XCC_ID, 0, 4)
	s_waitcnt vmcnt(0)
	s_waitcnt lgkmcnt(0)
	s_barrier
	s_and_saveexec_b64 s[6:7], s[44:45]
	s_cbranch_execz .LBB0_1495
	s_cmp_eq_u32 s99, 0
	s_cbranch_scc1 .Lfb_skip_6
	s_load_dwordx2 s[8:9], s[0:1], 0x80
	s_and_b32 s10, s2, 7
	s_lshl_b32 s10, s10, 8
	s_add_i32 s10, s10, 0x1000
	s_lshr_b32 s11, s2, 3
	s_lshl_b32 s11, s11, 2
	v_mov_b32_e32 v1, s11
	v_mov_b32_e32 v0, 7
	s_mov_b32 s13, 0
	s_mov_b64 s[16:17], exec
	s_waitcnt lgkmcnt(0)
	s_add_u32 s8, s8, s10
	s_addc_u32 s9, s9, 0
	global_store_dword v1, v0, s[8:9]
	buffer_inv sc1
	s_mov_b64 exec, 0xffffffff
	v_mbcnt_lo_u32_b32 v4, -1, 0
	v_lshlrev_b32_e32 v4, 2, v4
	v_mov_b32_e32 v0, 7
